# attention softmax path: drop redundant canonicalising max pairs and +0 row-sum initialisers
# speedup vs baseline: 1.0109x; 1.0043x over previous
; #define LAS __attribute__((address_space(3)))
; __device__ __forceinline__ float xhalf_max(float m) { auto rr = __builtin_amdgcn_permlane32_swap(__float_as_uint(m), __float_as_uint(m), false, false); return fmaxf(__uint_as_float(rr[0]), __uint_as_float(rr[1])); }
; #define SB() __builtin_amdgcn_sched_barrier(0)
; __device__ __forceinline__ void softmax_def(f32x16& p0, f32x16& p1, bool first, float cb, float& mref, f32x16& negm, float& l, f32x16& oa, f32x16& ob) {
;     float a = fmaxf(fmaxf(p0[0], p0[1]), p1[0]), b = fmaxf(fmaxf(p0[2], p0[3]), p1[1]);
;     a = fmaxf(fmaxf(a, p1[2]), p1[3]);
; #pragma unroll
;     for (int r = 4; r < 16; r += 4) { a = fmaxf(fmaxf(a, p0[r]), p0[r + 1]); b = fmaxf(fmaxf(b, p0[r + 2]), p0[r + 3]); a = fmaxf(fmaxf(a, p1[r]), p1[r + 1]); b = fmaxf(fmaxf(b, p1[r + 2]), p1[r + 3]); }
;     const float rm = xhalf_max(fmaxf(a, b));
; template <int MODE>
; __device__ __forceinline__ void attn_unit(LAS unsigned char* lds, const Ptrs& P, int nq, int nt_block, int qpos0, bool sample, int h,
;                                           const float* relb  , const float* lamp, const float* subg, bf16_t* Obase  , int wv) {
;     ...
;             if (MODE == 1) {
;                 f32x16 p0, p1;
;                 bf16x8 kf[12];
; #pragma unroll
;                 for (int ks = 0; ks < 6; ++ks) { kf[2 * ks] = *(const LAS bf16x8*)(kb + ks * 2048); kf[2 * ks + 1] = *(const LAS bf16x8*)(kb + ks * 2048 + 512); }
;                 SB();
;                 p0 = __builtin_amdgcn_mfma_f32_32x32x16_bf16(kf[0], qf[0], ng1, 0, 0, 0);
;                 p1 = __builtin_amdgcn_mfma_f32_32x32x16_bf16(kf[1], qf[0], ng1, 0, 0, 0);
; #pragma unroll
;                 for (int ks = 1; ks < 6; ++ks) {
;                     p0 = __builtin_amdgcn_mfma_f32_32x32x16_bf16(kf[2 * ks], qf[ks], p0, 0, 0, 0);
;                     p1 = __builtin_amdgcn_mfma_f32_32x32x16_bf16(kf[2 * ks + 1], qf[ks], p1, 0, 0, 0);
;                 }
;                 bf16x8 vf[8]; VLOAD(vf);
;                 softmax_def(p0, p1, first, 0.f, mr1, ng1, l1, o1a, o1b);
.LBB0_1199:
	s_or_b32 s36, s37, s46
	s_cmp_ge_i32 s4, s36
	s_cselect_b64 s[30:31], -1, 0
	s_and_b64 s[30:31], s[38:39], s[30:31]
	s_andn2_b64 vcc, exec, s[30:31]
	s_cbranch_vccnz .LBB0_1198
	s_mul_i32 s30, s37, 0x5000
	s_add_i32 s30, s44, s30
	v_add3_u32 v4, s30, v178, v179
	ds_read_b128 v[6:9], v4
	ds_read_b128 v[10:13], v4 offset:512
	ds_read_b128 v[14:17], v4 offset:2048
	ds_read_b128 v[144:147], v4 offset:2560
	ds_read_b128 v[148:151], v4 offset:4096
	ds_read_b128 v[152:155], v4 offset:4608
	ds_read_b128 v[156:159], v4 offset:6144
	ds_read_b128 v[160:163], v4 offset:6656
	ds_read_b128 v[180:183], v4 offset:8192
	ds_read_b128 v[184:187], v4 offset:8704
	ds_read_b128 v[188:191], v4 offset:10240
	ds_read_b128 v[192:195], v4 offset:10752
	v_add_u32_e32 v4, s30, v175
	v_add3_u32 v4, v4, v176, v172
	s_waitcnt lgkmcnt(11)
	v_mfma_f32_32x32x16_bf16 v[84:99], v[6:9], v[0:3], v[52:67]
	s_cmp_eq_u32 s36, 0
	s_cselect_b64 s[30:31], -1, 0
	s_cmp_lg_u32 s36, 0
	s_waitcnt lgkmcnt(10)
	v_mfma_f32_32x32x16_bf16 v[68:83], v[10:13], v[0:3], v[52:67]
	s_waitcnt lgkmcnt(9)
	v_mfma_f32_32x32x16_bf16 v[84:99], v[14:17], v[100:103], v[84:99]
	s_waitcnt lgkmcnt(8)
	v_mfma_f32_32x32x16_bf16 v[68:83], v[144:147], v[100:103], v[68:83]
	s_waitcnt lgkmcnt(7)
	v_mfma_f32_32x32x16_bf16 v[84:99], v[148:151], v[104:107], v[84:99]
	s_waitcnt lgkmcnt(6)
	v_mfma_f32_32x32x16_bf16 v[68:83], v[152:155], v[104:107], v[68:83]
	s_waitcnt lgkmcnt(5)
	v_mfma_f32_32x32x16_bf16 v[84:99], v[156:159], v[108:111], v[84:99]
	s_waitcnt lgkmcnt(4)
	v_mfma_f32_32x32x16_bf16 v[68:83], v[160:163], v[108:111], v[68:83]
	ds_read_b64_tr_b16 v[160:161], v4 offset:12288
	ds_read_b64_tr_b16 v[162:163], v4 offset:12800
	ds_read_b64_tr_b16 v[152:153], v4 offset:13312
	ds_read_b64_tr_b16 v[154:155], v4 offset:13824
	ds_read_b64_tr_b16 v[156:157], v4 offset:16384
	ds_read_b64_tr_b16 v[158:159], v4 offset:16896
	ds_read_b64_tr_b16 v[148:149], v4 offset:17408
	ds_read_b64_tr_b16 v[150:151], v4 offset:17920
	ds_read_b64_tr_b16 v[144:145], v4 offset:14336
	ds_read_b64_tr_b16 v[146:147], v4 offset:14848
	ds_read_b64_tr_b16 v[10:11], v4 offset:15360
	ds_read_b64_tr_b16 v[12:13], v4 offset:15872
	ds_read_b64_tr_b16 v[14:15], v4 offset:18432
	ds_read_b64_tr_b16 v[16:17], v4 offset:18944
	ds_read_b64_tr_b16 v[6:7], v4 offset:19456
	ds_read_b64_tr_b16 v[8:9], v4 offset:19968
	s_waitcnt lgkmcnt(14)
	v_mfma_f32_32x32x16_bf16 v[84:99], v[180:183], v[112:115], v[84:99]
	v_mfma_f32_32x32x16_bf16 v[68:83], v[184:187], v[112:115], v[68:83]
	v_mfma_f32_32x32x16_bf16 v[84:99], v[188:191], v[116:119], v[84:99]
	v_mfma_f32_32x32x16_bf16 v[68:83], v[192:195], v[116:119], v[68:83]
	s_nop 10
	v_max_f32_e32 v4, v84, v85
	v_max3_f32 v19, v86, v87, v69
	v_max3_f32 v4, v4, v68, v70
	v_max3_f32 v4, v4, v71, v88
	v_max3_f32 v19, v19, v90, v91
	v_max3_f32 v4, v4, v89, v72
	v_max3_f32 v19, v19, v74, v75
	v_max3_f32 v4, v4, v73, v92
	v_max3_f32 v19, v19, v94, v95
	v_max3_f32 v4, v4, v93, v76
	v_max3_f32 v19, v19, v78, v79
	v_max3_f32 v4, v4, v77, v96
	v_max3_f32 v19, v19, v98, v99
	v_max3_f32 v4, v4, v97, v80
	v_max3_f32 v19, v19, v82, v83
	v_max3_f32 v4, v4, v81, v19
	v_mov_b32_e32 v19, v4
	s_nop 1
	v_permlane32_swap_b32_e32 v4, v19
	v_max_f32_e32 v19, v4, v19
	s_cbranch_scc0 .LBB0_1208
	v_cmp_lt_f32_e32 vcc, s76, v19
	s_mov_b64 s[42:43], 0
	s_mov_b64 s[36:37], 0
	s_cbranch_vccz .LBB0_1207
	v_max_f32_e32 v4, v19, v19
	v_max_f32_e32 v4, 0, v4
	s_mov_b64 s[36:37], -1

; __device__ __forceinline__ unsigned cvtpk(float lo, float hi) { f32x2_t v = {lo, hi}; bf16x2_t b = __builtin_convertvector(v, bf16x2_t); return __builtin_bit_cast(unsigned, b); }
; __device__ __forceinline__ void softmax_def(f32x16& p0, f32x16& p1, bool first, float cb, float& mref, f32x16& negm, float& l, f32x16& oa, f32x16& ob) {
;     ...
;     float s0 = 0.f, s1 = 0.f, s2 = 0.f, s3 = 0.f;
; #pragma unroll
;     for (int r = 0; r < 16; ++r) { p0[r] = __builtin_amdgcn_exp2f(p0[r]); p1[r] = __builtin_amdgcn_exp2f(p1[r]); }
; #pragma unroll
;     for (int r = 0; r < 16; r += 2) { s0 += p0[r]; s1 += p0[r + 1]; s2 += p1[r]; s3 += p1[r + 1]; }
;     l += (s0 + s1) + (s2 + s3);
; }
; __device__ __forceinline__ void pack_p(const f32x16& p0, const f32x16& p1, bf16x8 (&pa)[4]) {
;     u32x4 w;
;     w.x = cvtpk(p0[0], p0[1]); w.y = cvtpk(p0[2], p0[3]); w.z = cvtpk(p0[4], p0[5]); w.w = cvtpk(p0[6], p0[7]); pa[0] = __builtin_bit_cast(bf16x8, w);
;     w.x = cvtpk(p0[8], p0[9]); w.y = cvtpk(p0[10], p0[11]); w.z = cvtpk(p0[12], p0[13]); w.w = cvtpk(p0[14], p0[15]); pa[1] = __builtin_bit_cast(bf16x8, w);
;     w.x = cvtpk(p1[0], p1[1]); w.y = cvtpk(p1[2], p1[3]); w.z = cvtpk(p1[4], p1[5]); w.w = cvtpk(p1[6], p1[7]); pa[2] = __builtin_bit_cast(bf16x8, w);
;     w.x = cvtpk(p1[8], p1[9]); w.y = cvtpk(p1[10], p1[11]); w.z = cvtpk(p1[12], p1[13]); w.w = cvtpk(p1[14], p1[15]); pa[3] = __builtin_bit_cast(bf16x8, w);
; }
; template <int MODE>
; __device__ __forceinline__ void attn_unit(LAS unsigned char* lds, const Ptrs& P, int nq, int nt_block, int qpos0, bool sample, int h,
;                                           const float* relb  , const float* lamp, const float* subg, bf16_t* Obase  , int wv) {
;     ...
;                 bf16x8 pa[4]; pack_p(p0, p1, pa);
; #pragma unroll
;                 for (int ks = 0; ks < 4; ++ks) {
;                     o1a = __builtin_amdgcn_mfma_f32_32x32x16_bf16(vf[2 * ks], pa[ks], o1a, 0, 0, 0);
;                     o1b = __builtin_amdgcn_mfma_f32_32x32x16_bf16(vf[2 * ks + 1], pa[ks], o1b, 0, 0, 0);
;                 }
.LBB0_1207:
	v_exp_f32_e32 v181, v84
	v_exp_f32_e32 v85, v85
	v_exp_f32_e32 v183, v86
	v_exp_f32_e32 v87, v87
	v_exp_f32_e32 v185, v88
	v_exp_f32_e32 v89, v89
	v_exp_f32_e32 v187, v90
	v_exp_f32_e32 v91, v91
	v_exp_f32_e32 v180, v68
	v_exp_f32_e32 v84, v69
	v_exp_f32_e32 v182, v70
	v_exp_f32_e32 v86, v71
	v_cvt_pk_bf16_f32 v68, v181, v85
	v_cvt_pk_bf16_f32 v69, v183, v87
	v_cvt_pk_bf16_f32 v70, v185, v89
	v_cvt_pk_bf16_f32 v71, v187, v91
	v_exp_f32_e32 v88, v73
	v_exp_f32_e32 v73, v92
	v_mfma_f32_32x32x16_bf16 v[36:51], v[160:163], v[68:71], v[36:51]
	v_exp_f32_e32 v93, v93
	v_exp_f32_e32 v161, v94
	v_exp_f32_e32 v95, v95
	v_exp_f32_e32 v163, v96
	v_exp_f32_e32 v97, v97
	v_exp_f32_e32 v99, v99
	v_exp_f32_e32 v184, v72
	s_waitcnt lgkmcnt(10)
	v_mfma_f32_32x32x16_bf16 v[20:35], v[156:159], v[68:71], v[20:35]
	v_exp_f32_e32 v157, v98
	v_cvt_pk_bf16_f32 v68, v73, v93
	v_cvt_pk_bf16_f32 v69, v161, v95
	v_cvt_pk_bf16_f32 v70, v163, v97
	v_cvt_pk_bf16_f32 v71, v157, v99
	v_exp_f32_e32 v186, v74
	v_exp_f32_e32 v90, v75
	v_mfma_f32_32x32x16_bf16 v[36:51], v[152:155], v[68:71], v[36:51]
	v_exp_f32_e32 v72, v76
	v_exp_f32_e32 v92, v77
	v_exp_f32_e32 v160, v78
	v_exp_f32_e32 v94, v79
	v_exp_f32_e32 v162, v80
	v_exp_f32_e32 v96, v81
	s_waitcnt lgkmcnt(8)
	v_mfma_f32_32x32x16_bf16 v[20:35], v[148:151], v[68:71], v[20:35]
	v_cvt_pk_bf16_f32 v68, v180, v84
	v_cvt_pk_bf16_f32 v69, v182, v86
	v_cvt_pk_bf16_f32 v70, v184, v88
	v_cvt_pk_bf16_f32 v71, v186, v90
	v_exp_f32_e32 v156, v82
	v_exp_f32_e32 v98, v83
	s_waitcnt lgkmcnt(6)
	v_mfma_f32_32x32x16_bf16 v[36:51], v[144:147], v[68:71], v[36:51]
	v_add_f32_e64 v74, v182, v180
	v_add_f32_e64 v75, v183, v181
	v_add_f32_e64 v76, v86, v84
	v_add_f32_e64 v77, v87, v85
	v_add_f32_e64 v74, v184, v74
	v_add_f32_e64 v75, v185, v75
	v_pk_add_f32 v[76:77], v[88:89], v[76:77]
	v_pk_add_f32 v[74:75], v[186:187], v[74:75]
	v_pk_add_f32 v[76:77], v[90:91], v[76:77]
	s_xor_b64 s[30:31], s[2:3], -1
	s_waitcnt lgkmcnt(2)
	v_mfma_f32_32x32x16_bf16 v[20:35], v[14:17], v[68:71], v[20:35]
	v_add_f32_e64 v14, v72, v74
	v_add_f32_e64 v15, v73, v75
	v_add_f32_e64 v68, v92, v76
	v_add_f32_e64 v69, v93, v77
	v_add_f32_e64 v70, v160, v14
	v_add_f32_e64 v71, v161, v15
	v_cvt_pk_bf16_f32 v14, v72, v92
	v_cvt_pk_bf16_f32 v15, v160, v94
	v_cvt_pk_bf16_f32 v16, v162, v96
	v_cvt_pk_bf16_f32 v17, v156, v98
	s_nop 1
	v_mfma_f32_32x32x16_bf16 v[36:51], v[10:13], v[14:17], v[36:51]
	v_add_f32_e64 v10, v94, v68
	v_add_f32_e64 v11, v95, v69
	v_add_f32_e64 v12, v162, v70
	v_add_f32_e64 v13, v163, v71
	v_add_f32_e64 v10, v96, v10
	v_add_f32_e64 v11, v97, v11
	v_pk_add_f32 v[12:13], v[156:157], v[12:13]
	v_pk_add_f32 v[10:11], v[98:99], v[10:11]
	s_nop 0
	v_pk_add_f32 v[10:11], v[10:11], v[12:13]
	s_waitcnt lgkmcnt(0)
	v_mfma_f32_32x32x16_bf16 v[20:35], v[6:9], v[14:17], v[20:35]
	v_add_f32_e32 v4, v10, v11
	v_add_f32_e32 v177, v177, v4
	s_mov_b32 s37, 1
	s_mov_b64 s[2:3], 0
	s_and_b64 vcc, exec, s[30:31]
	s_cbranch_vccz .LBB0_1199
	s_branch .LBB0_1209

; #define LAS __attribute__((address_space(3)))
; __device__ __forceinline__ float xhalf_max(float m) { auto rr = __builtin_amdgcn_permlane32_swap(__float_as_uint(m), __float_as_uint(m), false, false); return fmaxf(__uint_as_float(rr[0]), __uint_as_float(rr[1])); }
; __device__ __forceinline__ void softmax_def(f32x16& p0, f32x16& p1, bool first, float cb, float& mref, f32x16& negm, float& l, f32x16& oa, f32x16& ob) {
;     float a = fmaxf(fmaxf(p0[0], p0[1]), p1[0]), b = fmaxf(fmaxf(p0[2], p0[3]), p1[1]);
;     a = fmaxf(fmaxf(a, p1[2]), p1[3]);
; #pragma unroll
;     for (int r = 4; r < 16; r += 4) { a = fmaxf(fmaxf(a, p0[r]), p0[r + 1]); b = fmaxf(fmaxf(b, p0[r + 2]), p0[r + 3]); a = fmaxf(fmaxf(a, p1[r]), p1[r + 1]); b = fmaxf(fmaxf(b, p1[r + 2]), p1[r + 3]); }
;     const float rm = xhalf_max(fmaxf(a, b));
;     if (first || __any(rm > 16.f)) {
; template <int MODE>
; __device__ __forceinline__ void attn_unit(LAS unsigned char* lds, const Ptrs& P, int nq, int nt_block, int qpos0, bool sample, int h,
;                                           const float* relb  , const float* lamp, const float* subg, bf16_t* Obase  , int wv) {
;     ...
;                         p0 = __builtin_amdgcn_mfma_f32_32x32x16_bf16(kf[0], qf[0], p0, 0, 0, 0);
;                         p1 = __builtin_amdgcn_mfma_f32_32x32x16_bf16(kf[1], qf[0], p1, 0, 0, 0);
;                     }
;                     p0 = __builtin_amdgcn_mfma_f32_32x32x16_bf16(kf[2], qf[1], p0, 0, 0, 0);
;                     p1 = __builtin_amdgcn_mfma_f32_32x32x16_bf16(kf[3], qf[1], p1, 0, 0, 0);
; #pragma unroll
;                     for (int ks = 0; ks < 2; ++ks) { kg2[2 * ks] = *(const LAS bf16x8*)(kb + 4096 + ks * 2048); kg2[2 * ks + 1] = *(const LAS bf16x8*)(kb + 4096 + ks * 2048 + 512); }
.LBB0_1231:
	s_waitcnt lgkmcnt(1)
	v_mfma_f32_32x32x16_bf16 v[118:133], v[72:75], v[182:185], v[118:133]
	ds_read_b128 v[80:83], v4 offset:4096
	ds_read_b128 v[210:213], v4 offset:4608
	ds_read_b128 v[76:79], v4 offset:6144
	ds_read_b128 v[72:75], v4 offset:6656
	s_cmp_eq_u32 s28, 0
	s_cselect_b64 s[24:25], -1, 0
	s_cmp_lg_u32 s28, 0
	s_cselect_b64 s[2:3], -1, 0
	s_and_b64 vcc, exec, s[2:3]
	s_waitcnt lgkmcnt(4)
	v_mfma_f32_32x32x16_bf16 v[134:149], v[150:153], v[182:185], v[134:149]
	s_cmp_lg_u64 s[26:27], 0
	s_cbranch_scc1 .Lqk2h_skip_p
	s_waitcnt lgkmcnt(3)
	v_mfma_f32_32x32x16_bf16 v[166:181], v[80:83], v[186:189], v[86:101]
	s_waitcnt lgkmcnt(2)
	v_mfma_f32_32x32x16_bf16 v[150:165], v[210:213], v[186:189], v[86:101]
	s_waitcnt lgkmcnt(1)
	v_mfma_f32_32x32x16_bf16 v[166:181], v[76:79], v[190:193], v[166:181]
	s_waitcnt lgkmcnt(0)
	v_mfma_f32_32x32x16_bf16 v[150:165], v[72:75], v[190:193], v[150:165]
.Lqk2h_skip_p:
	v_max_f32_e32 v4, v118, v119
	s_nop 9
	v_max3_f32 v85, v120, v121, v135
	v_max3_f32 v4, v4, v134, v136
	v_max3_f32 v4, v4, v137, v122
	v_max3_f32 v85, v85, v124, v125
	v_max3_f32 v4, v4, v123, v138
	v_max3_f32 v85, v85, v140, v141
	v_max3_f32 v4, v4, v139, v126
	v_max3_f32 v85, v85, v128, v129
	v_max3_f32 v4, v4, v127, v142
	v_max3_f32 v85, v85, v144, v145
	v_max3_f32 v4, v4, v143, v130
	v_max3_f32 v85, v85, v132, v133
	v_max3_f32 v4, v4, v131, v146
	v_max3_f32 v85, v85, v148, v149
	v_max3_f32 v4, v4, v147, v85
	v_mov_b32_e32 v85, v4
	s_nop 1
	v_permlane32_swap_b32_e32 v4, v85
	v_max_f32_e32 v85, v4, v85
	s_cbranch_vccz .LBB0_1236
	v_cmp_lt_f32_e32 vcc, s76, v85
	s_mov_b64 s[30:31], 0
	s_mov_b64 s[28:29], 0
	s_cbranch_vccz .LBB0_1239
	v_max_f32_e32 v4, v85, v85
	v_max_f32_e32 v4, 0, v4
	s_mov_b64 s[28:29], -1

; __device__ __forceinline__ float xhalf_max(float m) { auto rr = __builtin_amdgcn_permlane32_swap(__float_as_uint(m), __float_as_uint(m), false, false); return fmaxf(__uint_as_float(rr[0]), __uint_as_float(rr[1])); }
; __device__ __forceinline__ void softmax_def(f32x16& p0, f32x16& p1, bool first, float cb, float& mref, f32x16& negm, float& l, f32x16& oa, f32x16& ob) {
;     float a = fmaxf(fmaxf(p0[0], p0[1]), p1[0]), b = fmaxf(fmaxf(p0[2], p0[3]), p1[1]);
;     a = fmaxf(fmaxf(a, p1[2]), p1[3]);
; #pragma unroll
;     for (int r = 4; r < 16; r += 4) { a = fmaxf(fmaxf(a, p0[r]), p0[r + 1]); b = fmaxf(fmaxf(b, p0[r + 2]), p0[r + 3]); a = fmaxf(fmaxf(a, p1[r]), p1[r + 1]); b = fmaxf(fmaxf(b, p1[r + 2]), p1[r + 3]); }
;     const float rm = xhalf_max(fmaxf(a, b));
;     if (first || __any(rm > 16.f)) {
; template <int MODE>
; __device__ __forceinline__ void attn_unit(LAS unsigned char* lds, const Ptrs& P, int nq, int nt_block, int qpos0, bool sample, int h,
;                                           const float* relb  , const float* lamp, const float* subg, bf16_t* Obase  , int wv) {
;     ...
;                     s0 = __builtin_amdgcn_mfma_f32_32x32x16_bf16(kg2[2], qf[3], s0, 0, 0, 0);
;                     s1 = __builtin_amdgcn_mfma_f32_32x32x16_bf16(kg2[3], qf[3], s1, 0, 0, 0);
;                     softmax_def(s0, s1, first, cbias, mr2, ng2, l2, o2a, o2b);
.LBB0_1243:
	s_waitcnt lgkmcnt(1)
	v_mfma_f32_32x32x16_bf16 v[166:181], v[76:79], v[190:193], v[166:181]
	s_and_b64 vcc, exec, s[2:3]
	s_waitcnt lgkmcnt(0)
	v_mfma_f32_32x32x16_bf16 v[150:165], v[72:75], v[190:193], v[150:165]
	s_nop 10
.Lqk2h_done_p:
	v_max_f32_e32 v4, v166, v167
	v_max3_f32 v72, v168, v169, v151
	v_max3_f32 v4, v4, v150, v152
	v_max3_f32 v4, v4, v153, v170
	v_max3_f32 v72, v72, v172, v173
	v_max3_f32 v4, v4, v171, v154
	v_max3_f32 v72, v72, v156, v157
	v_max3_f32 v4, v4, v155, v174
	v_max3_f32 v72, v72, v176, v177
	v_max3_f32 v4, v4, v175, v158
	v_max3_f32 v72, v72, v160, v161
	v_max3_f32 v4, v4, v159, v178
	v_max3_f32 v72, v72, v180, v181
	v_max3_f32 v4, v4, v179, v162
	v_max3_f32 v72, v72, v164, v165
	v_max3_f32 v4, v4, v163, v72
	v_mov_b32_e32 v72, v4
	s_nop 1
	v_permlane32_swap_b32_e32 v4, v72
	v_max_f32_e32 v72, v4, v72
	s_cbranch_vccz .LBB0_1251
	v_cmp_lt_f32_e32 vcc, s76, v72
	s_mov_b64 s[26:27], 0
	s_mov_b64 s[2:3], 0
	s_cbranch_vccz .LBB0_1250
	v_max_f32_e32 v4, v72, v72
	v_max_f32_e32 v4, 0, v4
	s_mov_b64 s[2:3], -1

; __device__ __forceinline__ unsigned cvtpk(float lo, float hi) { f32x2_t v = {lo, hi}; bf16x2_t b = __builtin_convertvector(v, bf16x2_t); return __builtin_bit_cast(unsigned, b); }
; __device__ __forceinline__ void softmax_def(f32x16& p0, f32x16& p1, bool first, float cb, float& mref, f32x16& negm, float& l, f32x16& oa, f32x16& ob) {
;     ...
;     float s0 = 0.f, s1 = 0.f, s2 = 0.f, s3 = 0.f;
; #pragma unroll
;     for (int r = 0; r < 16; ++r) { p0[r] = __builtin_amdgcn_exp2f(p0[r]); p1[r] = __builtin_amdgcn_exp2f(p1[r]); }
; #pragma unroll
;     for (int r = 0; r < 16; r += 2) { s0 += p0[r]; s1 += p0[r + 1]; s2 += p1[r]; s3 += p1[r + 1]; }
;     l += (s0 + s1) + (s2 + s3);
; }
; __device__ __forceinline__ void pack_p(const f32x16& p0, const f32x16& p1, bf16x8 (&pa)[4]) {
;     u32x4 w;
;     w.x = cvtpk(p0[0], p0[1]); w.y = cvtpk(p0[2], p0[3]); w.z = cvtpk(p0[4], p0[5]); w.w = cvtpk(p0[6], p0[7]); pa[0] = __builtin_bit_cast(bf16x8, w);
;     w.x = cvtpk(p0[8], p0[9]); w.y = cvtpk(p0[10], p0[11]); w.z = cvtpk(p0[12], p0[13]); w.w = cvtpk(p0[14], p0[15]); pa[1] = __builtin_bit_cast(bf16x8, w);
;     w.x = cvtpk(p1[0], p1[1]); w.y = cvtpk(p1[2], p1[3]); w.z = cvtpk(p1[4], p1[5]); w.w = cvtpk(p1[6], p1[7]); pa[2] = __builtin_bit_cast(bf16x8, w);
;     w.x = cvtpk(p1[8], p1[9]); w.y = cvtpk(p1[10], p1[11]); w.z = cvtpk(p1[12], p1[13]); w.w = cvtpk(p1[14], p1[15]); pa[3] = __builtin_bit_cast(bf16x8, w);
; }
; template <int MODE>
; __device__ __forceinline__ void attn_unit(LAS unsigned char* lds, const Ptrs& P, int nq, int nt_block, int qpos0, bool sample, int h,
;                                           const float* relb  , const float* lamp, const float* subg, bf16_t* Obase  , int wv) {
;     ...
;                     pack_p(s0, s1, pb);
;                 }
;                 VLOADH(vf, 0); VLOADH(vf, 1);
; #pragma unroll
;                 for (int ks = 0; ks < 4; ++ks) {
;                     o1a = __builtin_amdgcn_mfma_f32_32x32x16_bf16(vf[2 * ks], pa[ks], o1a, 0, 0, 0);
;                     o1b = __builtin_amdgcn_mfma_f32_32x32x16_bf16(vf[2 * ks + 1], pa[ks], o1b, 0, 0, 0);
;                     o2a = __builtin_amdgcn_mfma_f32_32x32x16_bf16(vf[2 * ks], pb[ks], o2a, 0, 0, 0);
;                     o2b = __builtin_amdgcn_mfma_f32_32x32x16_bf16(vf[2 * ks + 1], pb[ks], o2b, 0, 0, 0);
;                 }
.LBB0_1250:
	v_exp_f32_e32 v75, v119
	v_exp_f32_e32 v79, v121
	v_exp_f32_e32 v4, v134
	v_exp_f32_e32 v83, v123
	v_exp_f32_e32 v72, v135
	v_exp_f32_e32 v74, v136
	v_exp_f32_e32 v119, v125
	v_exp_f32_e32 v73, v118
	v_exp_f32_e32 v76, v137
	v_exp_f32_e32 v78, v138
	v_exp_f32_e32 v125, v127
	v_exp_f32_e32 v77, v120
	v_exp_f32_e32 v80, v139
	v_exp_f32_e32 v82, v140
	v_add_f32_e32 v136, v79, v75
	v_exp_f32_e32 v81, v122
	v_exp_f32_e32 v85, v124
	v_exp_f32_e32 v118, v141
	v_exp_f32_e32 v124, v142
	v_add_f32_e32 v136, v83, v136
	v_exp_f32_e32 v134, v143
	v_add_f32_e32 v137, v74, v4
	v_add_f32_e32 v136, v119, v136
	v_exp_f32_e32 v120, v148
	v_exp_f32_e32 v121, v133
	v_add_f32_e32 v138, v76, v72
	v_add_f32_e32 v137, v78, v137
	v_add_f32_e32 v148, v125, v136
	v_add_u32_e32 v136, s42, v230
	v_add_f32_e32 v133, v77, v73
	v_add_f32_e32 v138, v80, v138
	v_add_f32_e32 v137, v82, v137
	v_add3_u32 v210, v136, v231, v217
	v_exp_f32_e32 v123, v126
	v_exp_f32_e32 v127, v128
	v_exp_f32_e32 v84, v144
	v_exp_f32_e32 v126, v145
	v_exp_f32_e32 v135, v130
	v_exp_f32_e32 v128, v146
	v_exp_f32_e32 v130, v147
	v_exp_f32_e32 v122, v149
	v_add_f32_e32 v133, v81, v133
	v_add_f32_e32 v140, v118, v138
	v_add_f32_e32 v149, v124, v137
	ds_read_b64_tr_b16 v[136:137], v210 offset:12288
	ds_read_b64_tr_b16 v[138:139], v210 offset:12800
	ds_read_b64_tr_b16 v[144:145], v210 offset:16384
	ds_read_b64_tr_b16 v[146:147], v210 offset:16896
	v_add_f32_e32 v133, v85, v133
	v_add_f32_e32 v211, v134, v140
	v_cvt_pk_bf16_f32 v140, v73, v75
	v_cvt_pk_bf16_f32 v141, v77, v79
	v_cvt_pk_bf16_f32 v142, v81, v83
	v_cvt_pk_bf16_f32 v143, v85, v119
	v_exp_f32_e32 v119, v166
	v_exp_f32_e32 v79, v167
	v_exp_f32_e32 v77, v168
	v_exp_f32_e32 v75, v169
	v_exp_f32_e32 v73, v170
	v_exp_f32_e32 v85, v171
	v_exp_f32_e32 v83, v172
	v_exp_f32_e32 v81, v173
	v_exp_f32_e32 v129, v129
	v_exp_f32_e32 v131, v131
	v_exp_f32_e32 v132, v132
	s_waitcnt lgkmcnt(2)
	v_mfma_f32_32x32x16_bf16 v[38:53], v[136:139], v[140:143], v[38:53]
	v_add_f32_e32 v133, v123, v133
	v_add_f32_e32 v133, v127, v133
	v_add_f32_e32 v148, v129, v148
	v_add_f32_e32 v133, v135, v133
	v_add_f32_e32 v148, v131, v148
	v_add_f32_e32 v167, v132, v133
	v_exp_f32_e32 v133, v176
	s_waitcnt lgkmcnt(0)
	v_mfma_f32_32x32x16_bf16 v[22:37], v[144:147], v[140:143], v[22:37]
	v_cvt_pk_bf16_f32 v140, v119, v79
	v_cvt_pk_bf16_f32 v141, v77, v75
	v_cvt_pk_bf16_f32 v142, v73, v85
	v_cvt_pk_bf16_f32 v143, v83, v81
	v_add_f32_e32 v149, v84, v149
	v_add_f32_e32 v149, v128, v149
	s_xor_b64 s[2:3], s[22:23], -1
	v_mfma_f32_32x32x16_bf16 v[54:69], v[136:139], v[140:143], v[54:69]
	v_add_f32_e32 v136, v126, v211
	v_add_f32_e32 v166, v130, v136
	ds_read_b64_tr_b16 v[136:137], v210 offset:13312
	ds_read_b64_tr_b16 v[138:139], v210 offset:13824
	v_mfma_f32_32x32x16_bf16 v[6:21], v[144:147], v[140:143], v[6:21]
	ds_read_b64_tr_b16 v[144:145], v210 offset:17408
	ds_read_b64_tr_b16 v[146:147], v210 offset:17920
	v_cvt_pk_bf16_f32 v140, v123, v125
	v_cvt_pk_bf16_f32 v141, v127, v129
	v_cvt_pk_bf16_f32 v142, v135, v131
	v_cvt_pk_bf16_f32 v143, v132, v121
	v_add_f32_e32 v132, v121, v148
	v_exp_f32_e32 v131, v174
	v_exp_f32_e32 v135, v175
	v_exp_f32_e32 v123, v177
	v_exp_f32_e32 v121, v178
	v_exp_f32_e32 v129, v179
	v_exp_f32_e32 v127, v180
	v_exp_f32_e32 v125, v181
	s_waitcnt lgkmcnt(2)
	v_mfma_f32_32x32x16_bf16 v[38:53], v[136:139], v[140:143], v[38:53]
	v_add_f32_e32 v148, v120, v149
	v_add_f32_e32 v132, v132, v167
	s_waitcnt lgkmcnt(0)
	v_mfma_f32_32x32x16_bf16 v[22:37], v[144:147], v[140:143], v[22:37]
	v_cvt_pk_bf16_f32 v140, v131, v135
	v_cvt_pk_bf16_f32 v141, v133, v123
	v_cvt_pk_bf16_f32 v142, v121, v129
	v_cvt_pk_bf16_f32 v143, v127, v125
	s_nop 1
	v_mfma_f32_32x32x16_bf16 v[54:69], v[136:139], v[140:143], v[54:69]
	v_add_f32_e32 v136, v122, v166
	v_add_f32_e32 v136, v136, v148
	v_add_f32_e32 v132, v136, v132
	ds_read_b64_tr_b16 v[136:137], v210 offset:14336
	ds_read_b64_tr_b16 v[138:139], v210 offset:14848
	ds_read_b64_tr_b16 v[166:167], v210 offset:18432
	ds_read_b64_tr_b16 v[168:169], v210 offset:18944
	v_add_f32_e32 v71, v71, v132
	v_exp_f32_e32 v132, v160
	v_mfma_f32_32x32x16_bf16 v[6:21], v[144:147], v[140:143], v[6:21]
	v_cvt_pk_bf16_f32 v142, v78, v80
	v_cvt_pk_bf16_f32 v143, v82, v118
	v_exp_f32_e32 v118, v150
	v_exp_f32_e32 v78, v151
	v_cvt_pk_bf16_f32 v140, v4, v72
	v_cvt_pk_bf16_f32 v141, v74, v76
	v_cvt_pk_bf16_f32 v145, v84, v126
	v_exp_f32_e32 v76, v152
	v_exp_f32_e32 v74, v153
	v_exp_f32_e32 v72, v154
	v_exp_f32_e32 v84, v155
	v_exp_f32_e32 v82, v156
	v_exp_f32_e32 v80, v157
	v_cvt_pk_bf16_f32 v144, v124, v134
	s_waitcnt lgkmcnt(2)
	v_mfma_f32_32x32x16_bf16 v[38:53], v[136:139], v[140:143], v[38:53]
	v_cvt_pk_bf16_f32 v146, v128, v130
	v_exp_f32_e32 v130, v158
	v_exp_f32_e32 v134, v159
	v_cvt_pk_bf16_f32 v147, v120, v122
	v_exp_f32_e32 v122, v161
	v_exp_f32_e32 v120, v162
	v_exp_f32_e32 v128, v163
	s_waitcnt lgkmcnt(0)
	v_mfma_f32_32x32x16_bf16 v[22:37], v[166:169], v[140:143], v[22:37]
	v_cvt_pk_bf16_f32 v140, v118, v78
	v_cvt_pk_bf16_f32 v141, v76, v74
	v_cvt_pk_bf16_f32 v142, v72, v84
	v_cvt_pk_bf16_f32 v143, v82, v80
	v_pk_add_f32 v[76:77], v[76:77], v[118:119]
	v_pk_add_f32 v[74:75], v[74:75], v[78:79]
	v_mfma_f32_32x32x16_bf16 v[54:69], v[136:139], v[140:143], v[54:69]
	v_add_f32_e64 v72, v72, v76
	v_add_f32_e64 v73, v73, v77
	v_add_f32_e64 v74, v84, v74
	v_add_f32_e64 v75, v85, v75
	v_exp_f32_e32 v126, v164
	v_exp_f32_e32 v124, v165
	v_pk_add_f32 v[72:73], v[82:83], v[72:73]
	v_pk_add_f32 v[74:75], v[80:81], v[74:75]
	v_pk_add_f32 v[72:73], v[130:131], v[72:73]
	v_mfma_f32_32x32x16_bf16 v[6:21], v[166:169], v[140:143], v[6:21]
	v_add_f32_e64 v76, v134, v74
	v_add_f32_e64 v77, v135, v75
	ds_read_b64_tr_b16 v[136:137], v210 offset:15360
	ds_read_b64_tr_b16 v[138:139], v210 offset:15872
	ds_read_b64_tr_b16 v[140:141], v210 offset:19456
	ds_read_b64_tr_b16 v[142:143], v210 offset:19968
	v_pk_add_f32 v[78:79], v[132:133], v[72:73]
	v_pk_add_f32 v[76:77], v[122:123], v[76:77]
	v_pk_add_f32 v[78:79], v[120:121], v[78:79]
	v_pk_add_f32 v[76:77], v[128:129], v[76:77]
	v_pk_add_f32 v[78:79], v[126:127], v[78:79]
	v_pk_add_f32 v[76:77], v[124:125], v[76:77]
	v_cvt_pk_bf16_f32 v72, v130, v134
	v_pk_add_f32 v[76:77], v[76:77], v[78:79]
	v_cvt_pk_bf16_f32 v73, v132, v122
	v_cvt_pk_bf16_f32 v74, v120, v128
	v_cvt_pk_bf16_f32 v75, v126, v124
	v_add_f32_e32 v4, v76, v77
	s_waitcnt lgkmcnt(2)
	v_mfma_f32_32x32x16_bf16 v[38:53], v[136:139], v[144:147], v[38:53]
	v_add_f32_e32 v218, v218, v4
	s_waitcnt lgkmcnt(0)
	v_mfma_f32_32x32x16_bf16 v[22:37], v[140:143], v[144:147], v[22:37]
	v_mfma_f32_32x32x16_bf16 v[54:69], v[136:139], v[72:75], v[54:69]
	v_mfma_f32_32x32x16_bf16 v[6:21], v[140:143], v[72:75], v[6:21]
	s_mov_b32 s24, 1
	s_mov_b64 s[22:23], 0
	s_and_b64 vcc, exec, s[2:3]
	s_cbranch_vccz .LBB0_1226
	s_branch .LBB0_1252
